# phase_norm: touch the next row (cache prefetch issued after the current row's loads, waits relaxed accordingly)
# speedup vs baseline: 1.4400x; 1.0036x over previous
; DI unsigned pack2(float a, float b) { f2_t v = {a, b}; bf2_t r = __builtin_convertvector(v, bf2_t); return __builtin_bit_cast(unsigned, r); }
; DI float wave_sum(float v) { for (int o = 32; o > 0; o >>= 1) v += __shfl_xor(v, o); return v; }
; DI void rms_row_bf16(const float* __restrict__ src, const float* __restrict__ g, u16* __restrict__ dst, int lane) {
;   float4 v[4]; float ss = 0.f;
; #pragma unroll
;   for (int i = 0; i < 4; ++i) { v[i] = *(const float4*)(src + i * 256 + lane * 4); ss += v[i].x * v[i].x + v[i].y * v[i].y + v[i].z * v[i].z + v[i].w * v[i].w; }
;   ss = wave_sum(ss);
;   float rs = rsqrtf(ss * (1.f / 1024.f) + 1e-6f);
; #pragma unroll
;   for (int i = 0; i < 4; ++i) {
;     float4 gg = *(const float4*)(g + i * 256 + lane * 4);
;     uint2 o; o.x = pack2(v[i].x * rs * gg.x, v[i].y * rs * gg.y); o.y = pack2(v[i].z * rs * gg.z, v[i].w * rs * gg.w);
;     *(uint2*)(dst + i * 256 + lane * 4) = o;
;   }
; }
; DI void phase_norm(const Params& p, int L, int c) {
;     ...
;   for (int lr = blockIdx.x * 4 + w; lr < TC; lr += gridDim.x * 4) {
;     int gt = gtok(rw, c, lr);
;     rms_row_bf16(xs + (size_t)gt * 1024, p.norm_g + L * 1024, H + (size_t)lr * 1024, lane);
;   }
.LBB0_89:
	v_ashrrev_i32_e32 v23, 31, v22
	v_lshlrev_b64 v[22:23], 12, v[22:23]
	v_ashrrev_i32_e32 v17, 31, v16
	v_lshlrev_b64 v[32:33], 11, v[16:17]
	v_lshl_add_u64 v[22:23], v[18:19], 0, v[22:23]
	v_lshl_add_u64 v[48:49], v[20:21], 0, v[32:33]
	global_load_dwordx4 v[32:35], v[22:23], off
	global_load_dwordx4 v[36:39], v[22:23], off offset:1024
	global_load_dwordx4 v[40:43], v[22:23], off offset:2048
	global_load_dwordx4 v[44:47], v[22:23], off offset:3072
	v_readlane_b32 s8, v254, 18
	v_readlane_b32 s9, v253, 51
	s_nop 1
	v_add_u32_e32 v72, s8, v16
	v_add_u32_e32 v73, s9, v30
	s_movk_i32 s9, 0x3fff
	v_cmp_ge_i32_e32 vcc, s9, v72
	s_nop 1
	v_cndmask_b32_e32 v72, v16, v72, vcc
	v_cndmask_b32_e32 v73, v30, v73, vcc
	v_and_b32_e32 v74, 0xffffe000, v73
	v_and_b32_e32 v75, 0xfff, v72
	s_nop 0
	v_or3_b32 v74, v75, v74, s73
	v_add_u32_e32 v75, 0x4000, v72
	v_readlane_b32 s8, v254, 35
	v_readlane_b32 s9, v254, 36
	s_nop 1
	v_cndmask_b32_e64 v74, v75, v74, s[8:9]
	v_ashrrev_i32_e32 v75, 31, v74
	v_lshlrev_b64 v[74:75], 12, v[74:75]
	v_lshl_add_u64 v[74:75], v[18:19], 0, v[74:75]
	global_load_dwordx4 v[76:79], v[74:75], off
	global_load_dwordx4 v[76:79], v[74:75], off offset:1024
	global_load_dwordx4 v[76:79], v[74:75], off offset:2048
	global_load_dwordx4 v[76:79], v[74:75], off offset:3072
	s_mov_b32 s8, 0x800000
	s_waitcnt vmcnt(7)
	v_pk_mul_f32 v[50:51], v[32:33], v[32:33]
	v_pk_mul_f32 v[52:53], v[34:35], v[34:35]
	s_waitcnt vmcnt(6)
	v_pk_fma_f32 v[50:51], v[36:37], v[36:37], v[50:51]
	v_pk_fma_f32 v[52:53], v[38:39], v[38:39], v[52:53]
	s_waitcnt vmcnt(5)
	v_pk_fma_f32 v[50:51], v[40:41], v[40:41], v[50:51]
	v_pk_fma_f32 v[52:53], v[42:43], v[42:43], v[52:53]
	s_waitcnt vmcnt(4)
	v_pk_fma_f32 v[50:51], v[44:45], v[44:45], v[50:51]
	v_pk_fma_f32 v[52:53], v[46:47], v[46:47], v[52:53]
	s_nop 0
	v_pk_add_f32 v[50:51], v[50:51], v[52:53]
	s_nop 0
	v_add_f32_e32 v17, v50, v51
	ds_bpermute_b32 v22, v24, v17
	s_waitcnt lgkmcnt(0)
	v_add_f32_e32 v17, v17, v22
	ds_bpermute_b32 v22, v25, v17
	s_waitcnt lgkmcnt(0)
	v_add_f32_e32 v17, v17, v22
	ds_bpermute_b32 v22, v26, v17
	s_waitcnt lgkmcnt(0)
	v_add_f32_e32 v17, v17, v22
	ds_bpermute_b32 v22, v27, v17
	s_waitcnt lgkmcnt(0)
	v_add_f32_e32 v17, v17, v22
	ds_bpermute_b32 v22, v28, v17
	s_waitcnt lgkmcnt(0)
	v_add_f32_e32 v17, v17, v22
	ds_bpermute_b32 v22, v29, v17
	s_waitcnt lgkmcnt(0)
	v_add_f32_e32 v17, v17, v22
	v_fmamk_f32 v17, v17, 0x3a800000, v206
	v_cmp_gt_f32_e32 vcc, s8, v17
	v_mul_f32_e32 v22, 0x4b800000, v17
	v_readlane_b32 s8, v254, 18
	v_cndmask_b32_e32 v17, v17, v22, vcc
	v_rsq_f32_e32 v17, v17
	v_add_u32_e32 v16, s8, v16
	v_readlane_b32 s8, v253, 51
	v_readlane_b32 s9, v254, 19
	v_mul_f32_e32 v22, 0x45800000, v17
	v_cndmask_b32_e32 v22, v17, v22, vcc
	v_pk_mul_f32 v[32:33], v[32:33], v[22:23] op_sel_hi:[1,0]
	v_pk_mul_f32 v[34:35], v[34:35], v[22:23] op_sel_hi:[1,0]
	v_pk_mul_f32 v[32:33], v[0:1], v[32:33]
	v_pk_mul_f32 v[34:35], v[2:3], v[34:35]
	v_cvt_pk_bf16_f32 v32, v32, v33
	v_cvt_pk_bf16_f32 v33, v34, v35
	global_store_dwordx2 v[48:49], v[32:33], off
	v_pk_mul_f32 v[32:33], v[36:37], v[22:23] op_sel_hi:[1,0]
	v_pk_mul_f32 v[34:35], v[38:39], v[22:23] op_sel_hi:[1,0]
	v_pk_mul_f32 v[32:33], v[4:5], v[32:33]
	v_pk_mul_f32 v[34:35], v[6:7], v[34:35]
	v_cvt_pk_bf16_f32 v32, v32, v33
	v_cvt_pk_bf16_f32 v33, v34, v35
	global_store_dwordx2 v[48:49], v[32:33], off offset:512
	v_pk_mul_f32 v[32:33], v[40:41], v[22:23] op_sel_hi:[1,0]
	v_pk_mul_f32 v[34:35], v[42:43], v[22:23] op_sel_hi:[1,0]
	v_pk_mul_f32 v[32:33], v[32:33], v[8:9]
	v_pk_mul_f32 v[34:35], v[34:35], v[10:11]
	v_cvt_pk_bf16_f32 v32, v32, v33
	v_cvt_pk_bf16_f32 v33, v34, v35
	global_store_dwordx2 v[48:49], v[32:33], off offset:1024
	v_pk_mul_f32 v[32:33], v[44:45], v[22:23] op_sel_hi:[1,0]
	v_pk_mul_f32 v[22:23], v[46:47], v[22:23] op_sel_hi:[1,0]
	v_add_u32_e32 v30, s8, v30
	s_movk_i32 s8, 0x3fff
	v_pk_mul_f32 v[32:33], v[32:33], v[12:13]
	v_pk_mul_f32 v[22:23], v[22:23], v[14:15]
	v_cmp_lt_i32_e32 vcc, s8, v16
	v_cvt_pk_bf16_f32 v32, v32, v33
	v_cvt_pk_bf16_f32 v33, v22, v23
	s_or_b64 s[6:7], vcc, s[6:7]
	global_store_dwordx2 v[48:49], v[32:33], off offset:1536
	s_andn2_b64 exec, exec, s[6:7]
	s_cbranch_execz .LBB0_94

; DI void phase_norm(const Params& p, int L, int c) {
;     ...
;   for (int lr = blockIdx.x * 4 + w; lr < TC; lr += gridDim.x * 4) {
;     int gt = gtok(rw, c, lr);
.LBB0_92:
	s_andn2_b64 vcc, exec, s[8:9]
	s_cbranch_vccnz .LBB0_89
	v_add_u32_e32 v22, 0x4000, v16
	s_branch .LBB0_89
.LBB0_94:
	s_or_b64 exec, exec, s[0:1]
	s_waitcnt vmcnt(0)
.LBB0_95:
	s_mov_b64 s[0:1], 0

; DI unsigned pack2(float a, float b) { f2_t v = {a, b}; bf2_t r = __builtin_convertvector(v, bf2_t); return __builtin_bit_cast(unsigned, r); }
; DI float wave_sum(float v) { for (int o = 32; o > 0; o >>= 1) v += __shfl_xor(v, o); return v; }
; DI void rms_row_bf16(const float* __restrict__ src, const float* __restrict__ g, u16* __restrict__ dst, int lane) {
;   float4 v[4]; float ss = 0.f;
; #pragma unroll
;   for (int i = 0; i < 4; ++i) { v[i] = *(const float4*)(src + i * 256 + lane * 4); ss += v[i].x * v[i].x + v[i].y * v[i].y + v[i].z * v[i].z + v[i].w * v[i].w; }
;   ss = wave_sum(ss);
;   float rs = rsqrtf(ss * (1.f / 1024.f) + 1e-6f);
; #pragma unroll
;   for (int i = 0; i < 4; ++i) {
;     float4 gg = *(const float4*)(g + i * 256 + lane * 4);
;     uint2 o; o.x = pack2(v[i].x * rs * gg.x, v[i].y * rs * gg.y); o.y = pack2(v[i].z * rs * gg.z, v[i].w * rs * gg.w);
;     *(uint2*)(dst + i * 256 + lane * 4) = o;
;   }
; }
; DI void phase_norm(const Params& p, int L, int c) {
;     ...
;   for (int lr = blockIdx.x * 4 + w; lr < TC; lr += gridDim.x * 4) {
;     int gt = gtok(rw, c, lr);
;     rms_row_bf16(xs + (size_t)gt * 1024, p.norm_g + L * 1024, H + (size_t)lr * 1024, lane);
;   }
.LBB0_618:
	v_ashrrev_i32_e32 v23, 31, v22
	v_lshlrev_b64 v[22:23], 12, v[22:23]
	v_ashrrev_i32_e32 v17, 31, v16
	v_lshlrev_b64 v[32:33], 11, v[16:17]
	v_lshl_add_u64 v[22:23], v[18:19], 0, v[22:23]
	v_lshl_add_u64 v[48:49], v[20:21], 0, v[32:33]
	global_load_dwordx4 v[32:35], v[22:23], off
	global_load_dwordx4 v[36:39], v[22:23], off offset:1024
	global_load_dwordx4 v[40:43], v[22:23], off offset:2048
	global_load_dwordx4 v[44:47], v[22:23], off offset:3072
	v_readlane_b32 s9, v253, 51
	s_nop 1
	v_add_u32_e32 v72, s26, v16
	v_add_u32_e32 v73, s9, v30
	s_movk_i32 s9, 0x3fff
	v_cmp_ge_i32_e32 vcc, s9, v72
	s_nop 1
	v_cndmask_b32_e32 v72, v16, v72, vcc
	v_cndmask_b32_e32 v73, v30, v73, vcc
	v_readlane_b32 s8, v255, 13
	v_readlane_b32 s9, v254, 53
	v_and_b32_e32 v74, 0xffffe000, v73
	v_and_b32_e32 v75, 0xfff, v72
	s_nop 0
	v_or3_b32 v74, v75, v74, s8
	v_add_u32_e32 v75, s9, v72
	v_readlane_b32 s8, v254, 35
	v_readlane_b32 s9, v254, 36
	s_nop 1
	v_cndmask_b32_e64 v74, v75, v74, s[8:9]
	v_ashrrev_i32_e32 v75, 31, v74
	v_lshlrev_b64 v[74:75], 12, v[74:75]
	v_lshl_add_u64 v[74:75], v[18:19], 0, v[74:75]
	global_load_dwordx4 v[76:79], v[74:75], off
	global_load_dwordx4 v[76:79], v[74:75], off offset:1024
	global_load_dwordx4 v[76:79], v[74:75], off offset:2048
	global_load_dwordx4 v[76:79], v[74:75], off offset:3072
	s_mov_b32 s8, 0x800000
	v_add_u32_e32 v16, s26, v16
	s_waitcnt vmcnt(7)
	v_pk_mul_f32 v[50:51], v[32:33], v[32:33]
	v_pk_mul_f32 v[52:53], v[34:35], v[34:35]
	s_waitcnt vmcnt(6)
	v_pk_fma_f32 v[50:51], v[36:37], v[36:37], v[50:51]
	v_pk_fma_f32 v[52:53], v[38:39], v[38:39], v[52:53]
	s_waitcnt vmcnt(5)
	v_pk_fma_f32 v[50:51], v[40:41], v[40:41], v[50:51]
	v_pk_fma_f32 v[52:53], v[42:43], v[42:43], v[52:53]
	s_waitcnt vmcnt(4)
	v_pk_fma_f32 v[50:51], v[44:45], v[44:45], v[50:51]
	v_pk_fma_f32 v[52:53], v[46:47], v[46:47], v[52:53]
	s_nop 0
	v_pk_add_f32 v[50:51], v[50:51], v[52:53]
	s_nop 0
	v_add_f32_e32 v17, v50, v51
	ds_bpermute_b32 v22, v24, v17
	s_waitcnt lgkmcnt(0)
	v_add_f32_e32 v17, v17, v22
	ds_bpermute_b32 v22, v25, v17
	s_waitcnt lgkmcnt(0)
	v_add_f32_e32 v17, v17, v22
	ds_bpermute_b32 v22, v26, v17
	s_waitcnt lgkmcnt(0)
	v_add_f32_e32 v17, v17, v22
	ds_bpermute_b32 v22, v27, v17
	s_waitcnt lgkmcnt(0)
	v_add_f32_e32 v17, v17, v22
	ds_bpermute_b32 v22, v28, v17
	s_waitcnt lgkmcnt(0)
	v_add_f32_e32 v17, v17, v22
	ds_bpermute_b32 v22, v29, v17
	s_waitcnt lgkmcnt(0)
	v_add_f32_e32 v17, v17, v22
	v_fmamk_f32 v17, v17, 0x3a800000, v206
	v_cmp_gt_f32_e32 vcc, s8, v17
	v_mul_f32_e32 v22, 0x4b800000, v17
	v_readlane_b32 s8, v253, 51
	v_cndmask_b32_e32 v17, v17, v22, vcc
	v_rsq_f32_e32 v17, v17
	v_add_u32_e32 v30, s8, v30
	s_movk_i32 s8, 0x3fff
	v_mul_f32_e32 v22, 0x45800000, v17
	v_cndmask_b32_e32 v22, v17, v22, vcc
	v_pk_mul_f32 v[32:33], v[32:33], v[22:23] op_sel_hi:[1,0]
	v_pk_mul_f32 v[34:35], v[34:35], v[22:23] op_sel_hi:[1,0]
	v_pk_mul_f32 v[32:33], v[0:1], v[32:33]
	v_pk_mul_f32 v[34:35], v[2:3], v[34:35]
	v_cvt_pk_bf16_f32 v32, v32, v33
	v_cvt_pk_bf16_f32 v33, v34, v35
	global_store_dwordx2 v[48:49], v[32:33], off
	v_pk_mul_f32 v[32:33], v[36:37], v[22:23] op_sel_hi:[1,0]
	v_pk_mul_f32 v[34:35], v[38:39], v[22:23] op_sel_hi:[1,0]
	v_pk_mul_f32 v[32:33], v[4:5], v[32:33]
	v_pk_mul_f32 v[34:35], v[6:7], v[34:35]
	v_cvt_pk_bf16_f32 v32, v32, v33
	v_cvt_pk_bf16_f32 v33, v34, v35
	global_store_dwordx2 v[48:49], v[32:33], off offset:512
	v_pk_mul_f32 v[32:33], v[40:41], v[22:23] op_sel_hi:[1,0]
	v_pk_mul_f32 v[34:35], v[42:43], v[22:23] op_sel_hi:[1,0]
	v_pk_mul_f32 v[32:33], v[32:33], v[8:9]
	v_pk_mul_f32 v[34:35], v[34:35], v[10:11]
	v_cvt_pk_bf16_f32 v32, v32, v33
	v_cvt_pk_bf16_f32 v33, v34, v35
	global_store_dwordx2 v[48:49], v[32:33], off offset:1024
	v_pk_mul_f32 v[32:33], v[44:45], v[22:23] op_sel_hi:[1,0]
	v_pk_mul_f32 v[22:23], v[46:47], v[22:23] op_sel_hi:[1,0]
	v_pk_mul_f32 v[32:33], v[32:33], v[12:13]
	v_pk_mul_f32 v[22:23], v[22:23], v[14:15]
	v_cmp_lt_i32_e32 vcc, s8, v16
	v_cvt_pk_bf16_f32 v32, v32, v33
	v_cvt_pk_bf16_f32 v33, v22, v23
	s_or_b64 s[6:7], vcc, s[6:7]
	global_store_dwordx2 v[48:49], v[32:33], off offset:1536
	s_andn2_b64 exec, exec, s[6:7]
	s_cbranch_execz .LBB0_623

; DI void phase_norm(const Params& p, int L, int c) {
;     ...
;   for (int lr = blockIdx.x * 4 + w; lr < TC; lr += gridDim.x * 4) {
;     int gt = gtok(rw, c, lr);
;     rms_row_bf16(xs + (size_t)gt * 1024, p.norm_g + L * 1024, H + (size_t)lr * 1024, lane);
;   }
.LBB0_623:
	s_or_b64 exec, exec, s[0:1]
	s_waitcnt vmcnt(0)
	v_readlane_b32 s0, v255, 15
	v_readlane_b32 s1, v255, 16
	s_andn2_b64 vcc, exec, s[0:1]
	s_cbranch_vccz .LBB0_656
